# attention: delayed V-tile ds_writes moved from the start of each half-step (ahead of the first K-fragment reads in the LDS queue) to behind the last K-fragment read pair
# speedup vs baseline: 1.0029x; 1.0029x over previous
; __device__ __forceinline__ void finishSM(f32x16& p0, f32x16& p1, float alpha, float& l_reg, bf16x8& pa0, bf16x8& pa1, bf16x8& pa2, bf16x8& pa3) {
;     for (int r = 0; r < 16; ++r) p1[r] = __builtin_amdgcn_exp2f(p1[r]);
;     float ps = 0; for (int r = 0; r < 16; ++r) ps += p0[r]; for (int r = 0; r < 16; ++r) ps += p1[r];
;     { auto rr = __builtin_amdgcn_permlane32_swap(__float_as_uint(ps), __float_as_uint(ps), false, false);
;       ps = __uint_as_float(rr[0]) + __uint_as_float(rr[1]); }
;     l_reg = l_reg * alpha + ps;
;     ...
;     PK4(p0, 0, pa0); PK4(p0, 8, pa1); PK4(p1, 0, pa2); PK4(p1, 8, pa3);
;     ...
; }
; template <int KB>
; __device__ __forceinline__ void qkt(f32x16& p0, f32x16& p1, const char* K_lds, int r32, int hi, const bf16x8* qr) {
;     p0 = f32x16{}; p1 = f32x16{};
;     const char* kb[4];
; #pragma unroll
;     for (int dd = 0; dd < 4; ++dd) kb[dd] = K_lds + KB * SHM_K + KSWZ(r32, (dd * 16 + hi * 8) * 2);
; #pragma unroll
;     for (int d0 = 0; d0 < 8; ++d0) { const char* a = kb[d0 & 3] + (d0 >> 2) * 128;
;         bf16x8 b0 = *reinterpret_cast<const bf16x8*>(a);
;         bf16x8 b1 = *reinterpret_cast<const bf16x8*>(a + 32 * 256);
;         p0 = __builtin_amdgcn_mfma_f32_32x32x16_bf16(b0, qr[d0], p0, 0, 0, 0);
;         p1 = __builtin_amdgcn_mfma_f32_32x32x16_bf16(b1, qr[d0], p1, 0, 0, 0); }
.LBB0_89:
	s_waitcnt vmcnt(0)
	ds_read_b128 v[66:69], v169 offset:49152
	ds_read_b128 v[70:73], v169 offset:57344
	ds_read_b128 v[100:103], v193 offset:49152
	ds_read_b128 v[136:139], v193 offset:57344
	v_add_f32_e32 v148, 0, v231
	v_add_f32_e32 v148, v233, v148
	v_add_f32_e32 v148, v229, v148
	v_add_f32_e32 v148, v232, v148
	v_add_f32_e32 v148, v228, v148
	v_add_f32_e32 v148, v230, v148
	v_add_f32_e32 v148, v226, v148
	v_add_f32_e32 v148, v227, v148
	v_add_f32_e32 v148, v223, v148
	v_add_f32_e32 v148, v225, v148
	v_add_f32_e32 v148, v209, v148
	v_add_f32_e32 v148, v224, v148
	v_add_f32_e32 v148, v206, v148
	v_add_f32_e32 v148, v208, v148
	v_add_f32_e32 v148, v205, v148
	v_add_f32_e32 v148, v207, v148
	v_exp_f32_e32 v140, v152
	v_exp_f32_e32 v141, v153
	v_exp_f32_e32 v142, v180
	v_exp_f32_e32 v143, v181
	s_waitcnt lgkmcnt(3)
	v_mfma_f32_32x32x16_bf16 v[82:97], v[66:69], v[132:135], 0
	v_exp_f32_e32 v144, v160
	v_exp_f32_e32 v145, v161
	v_exp_f32_e32 v146, v154
	v_exp_f32_e32 v147, v155
	s_waitcnt lgkmcnt(2)
	v_mfma_f32_32x32x16_bf16 v[66:81], v[70:73], v[132:135], 0
	v_exp_f32_e32 v178, v178
	v_exp_f32_e32 v179, v179
	v_exp_f32_e32 v162, v162
	v_exp_f32_e32 v163, v163
	s_waitcnt lgkmcnt(1)
	v_mfma_f32_32x32x16_bf16 v[82:97], v[100:103], v[128:131], v[82:97]
	v_add_f32_e32 v148, v178, v148
	v_add_f32_e32 v148, v179, v148
	v_add_f32_e32 v148, v162, v148
	v_exp_f32_e32 v158, v158
	s_waitcnt lgkmcnt(0)
	v_mfma_f32_32x32x16_bf16 v[66:81], v[136:139], v[128:131], v[66:81]
	v_exp_f32_e32 v159, v159
	v_exp_f32_e32 v156, v156
	v_exp_f32_e32 v157, v157
	v_add_f32_e32 v148, v163, v148
	ds_read_b128 v[100:103], v194 offset:49152
	ds_read_b128 v[136:139], v194 offset:57344
	s_waitcnt lgkmcnt(1)
	v_mfma_f32_32x32x16_bf16 v[82:97], v[100:103], v[124:127], v[82:97]
	v_add_f32_e32 v148, v158, v148
	v_add_f32_e32 v148, v159, v148
	v_add_f32_e32 v148, v156, v148
	v_add_f32_e32 v148, v157, v148
	s_waitcnt lgkmcnt(0)
	v_mfma_f32_32x32x16_bf16 v[66:81], v[136:139], v[124:127], v[66:81]
	v_add_f32_e32 v148, v140, v148
	v_add_f32_e32 v148, v141, v148
	v_add_f32_e32 v148, v142, v148
	v_add_f32_e32 v148, v143, v148
	ds_read_b128 v[100:103], v195 offset:49152
	ds_read_b128 v[136:139], v195 offset:57344
	s_waitcnt lgkmcnt(1)
	v_mfma_f32_32x32x16_bf16 v[82:97], v[100:103], v[120:123], v[82:97]
	v_add_f32_e32 v148, v144, v148
	v_add_f32_e32 v148, v145, v148
	v_add_f32_e32 v148, v146, v148
	v_add_f32_e32 v199, v147, v148
	s_waitcnt lgkmcnt(0)
	v_mfma_f32_32x32x16_bf16 v[66:81], v[136:139], v[120:123], v[66:81]
	v_mov_b32_e32 v200, v199
	s_nop 1
	v_permlane32_swap_b32_e32 v199, v200
	v_cvt_pk_bf16_f32 v148, v231, v233
	v_cvt_pk_bf16_f32 v149, v229, v232
	v_cvt_pk_bf16_f32 v150, v228, v230
	ds_read_b128 v[100:103], v169 offset:49280
	ds_read_b128 v[136:139], v169 offset:57472
	s_waitcnt lgkmcnt(1)
	v_mfma_f32_32x32x16_bf16 v[82:97], v[100:103], v[116:119], v[82:97]
	v_cvt_pk_bf16_f32 v151, v226, v227
	v_cvt_pk_bf16_f32 v152, v223, v225
	v_cvt_pk_bf16_f32 v153, v209, v224
	s_waitcnt lgkmcnt(0)
	v_mfma_f32_32x32x16_bf16 v[66:81], v[136:139], v[116:119], v[66:81]
	v_cvt_pk_bf16_f32 v154, v206, v208
	v_cvt_pk_bf16_f32 v155, v205, v207
	v_cvt_pk_bf16_f32 v158, v158, v159
	ds_read_b128 v[100:103], v193 offset:49280
	ds_read_b128 v[136:139], v193 offset:57472
	s_waitcnt lgkmcnt(1)
	v_mfma_f32_32x32x16_bf16 v[82:97], v[100:103], v[112:115], v[82:97]
	v_cvt_pk_bf16_f32 v159, v156, v157
	v_cvt_pk_bf16_f32 v156, v178, v179
	v_cvt_pk_bf16_f32 v157, v162, v163
	s_waitcnt lgkmcnt(0)
	v_mfma_f32_32x32x16_bf16 v[66:81], v[136:139], v[112:115], v[66:81]
	v_cvt_pk_bf16_f32 v160, v140, v141
	v_cvt_pk_bf16_f32 v161, v142, v143
	v_cvt_pk_bf16_f32 v162, v144, v145
	ds_read_b128 v[100:103], v194 offset:49280
	ds_read_b128 v[136:139], v194 offset:57472
	s_waitcnt lgkmcnt(1)
	v_mfma_f32_32x32x16_bf16 v[82:97], v[100:103], v[108:111], v[82:97]
	v_cvt_pk_bf16_f32 v163, v146, v147
	s_nop 0
	v_permlane32_swap_b32_e32 v148, v150
	v_permlane32_swap_b32_e32 v149, v151
	s_waitcnt lgkmcnt(0)
	v_mfma_f32_32x32x16_bf16 v[66:81], v[136:139], v[108:111], v[66:81]
	v_permlane32_swap_b32_e32 v152, v154
	v_permlane32_swap_b32_e32 v153, v155
	v_permlane32_swap_b32_e32 v156, v158
	ds_read_b128 v[100:103], v195 offset:49280
	ds_read_b128 v[136:139], v195 offset:57472
	s_cmp_eq_u32 s100, 0
	s_cbranch_scc1 .Lmy_hs1_nov
	ds_write_b128 v191, v[242:245] offset:16384
	ds_write_b128 v192, v[246:249] offset:16384
; template <int VB>
; __device__ __forceinline__ void pv_tile(f32x16* o, int vb0, bf16x8 pa0, bf16x8 pa1, bf16x8 pa2, bf16x8 pa3) {
;     ...
;     PV_D0(0); PV_D0(1); PV_D0(2); PV_D0(3);
.Lmy_hs1_nov:
	s_mov_b32 s100, 0
	ds_read_b64_tr_b16 v[172:173], v185 offset:0
	ds_read_b64_tr_b16 v[174:175], v185 offset:0x800
	ds_read_b64_tr_b16 v[202:203], v185 offset:0x1000
	ds_read_b64_tr_b16 v[204:205], v185 offset:0x1800
	ds_read_b64_tr_b16 v[206:207], v185 offset:0x2000
	ds_read_b64_tr_b16 v[208:209], v185 offset:0x2800
	ds_read_b64_tr_b16 v[224:225], v185 offset:0x3000
	ds_read_b64_tr_b16 v[226:227], v185 offset:0x3800
	s_waitcnt lgkmcnt(9)
	v_mfma_f32_32x32x16_bf16 v[82:97], v[100:103], v[104:107], v[82:97]
	v_permlane32_swap_b32_e32 v157, v159
	v_permlane32_swap_b32_e32 v160, v162
	v_permlane32_swap_b32_e32 v161, v163
	s_waitcnt lgkmcnt(8)
	v_mfma_f32_32x32x16_bf16 v[66:81], v[136:139], v[104:107], v[66:81]
	v_add_u32_e32 v178, s7, v166
	v_add_u32_e32 v100, 1, v178
	v_add_u32_e32 v102, 33, v178
	v_ashrrev_i32_e32 v101, 31, v100
	v_ashrrev_i32_e32 v103, 31, v102
	v_lshlrev_b64 v[140:141], 8, v[100:101]
	v_lshlrev_b64 v[142:143], 8, v[102:103]
	v_lshl_add_u64 v[100:101], v[170:171], 0, v[140:141]
	v_lshl_add_u64 v[136:137], v[170:171], 0, v[142:143]
	v_lshl_add_u64 v[140:141], v[176:177], 0, v[140:141]
	v_lshl_add_u64 v[144:145], v[176:177], 0, v[142:143]
	global_load_dwordx4 v[100:103], v[100:101], off
	s_nop 0
	global_load_dwordx4 v[136:139], v[136:137], off
	s_nop 0
	global_load_dwordx4 v[140:143], v[140:141], off
	s_nop 0
	global_load_dwordx4 v[144:147], v[144:145], off
	s_waitcnt lgkmcnt(0)
	s_nop 0
	v_mfma_f32_32x32x16_bf16 v[50:65], v[148:151], v[172:175], v[50:65]
	ds_read_b64_tr_b16 v[172:173], v185 offset:0x200
	ds_read_b64_tr_b16 v[174:175], v185 offset:0xa00
	v_mfma_f32_32x32x16_bf16 v[50:65], v[152:155], v[202:205], v[50:65]
	ds_read_b64_tr_b16 v[202:203], v185 offset:0x1200
	ds_read_b64_tr_b16 v[204:205], v185 offset:0x1a00
	v_mfma_f32_32x32x16_bf16 v[50:65], v[156:159], v[206:209], v[50:65]
	ds_read_b64_tr_b16 v[206:207], v185 offset:0x2200
	ds_read_b64_tr_b16 v[208:209], v185 offset:0x2a00
	v_mfma_f32_32x32x16_bf16 v[50:65], v[160:163], v[224:227], v[50:65]
	ds_read_b64_tr_b16 v[224:225], v185 offset:0x3200
	ds_read_b64_tr_b16 v[226:227], v185 offset:0x3a00
	s_waitcnt lgkmcnt(0)
	v_mfma_f32_32x32x16_bf16 v[34:49], v[148:151], v[172:175], v[34:49]
	ds_read_b64_tr_b16 v[172:173], v185 offset:0x400
	ds_read_b64_tr_b16 v[174:175], v185 offset:0xc00
	v_mfma_f32_32x32x16_bf16 v[34:49], v[152:155], v[202:205], v[34:49]
	ds_read_b64_tr_b16 v[202:203], v185 offset:0x1400
	ds_read_b64_tr_b16 v[204:205], v185 offset:0x1c00
	v_mfma_f32_32x32x16_bf16 v[34:49], v[156:159], v[206:209], v[34:49]
	ds_read_b64_tr_b16 v[206:207], v185 offset:0x2400
	ds_read_b64_tr_b16 v[208:209], v185 offset:0x2c00
	v_mfma_f32_32x32x16_bf16 v[34:49], v[160:163], v[224:227], v[34:49]
	ds_read_b64_tr_b16 v[224:225], v185 offset:0x3400
	ds_read_b64_tr_b16 v[226:227], v185 offset:0x3c00
	s_waitcnt lgkmcnt(0)
	v_mfma_f32_32x32x16_bf16 v[18:33], v[148:151], v[172:175], v[18:33]
	ds_read_b64_tr_b16 v[172:173], v185 offset:0x600
	ds_read_b64_tr_b16 v[174:175], v185 offset:0xe00
	v_mfma_f32_32x32x16_bf16 v[18:33], v[152:155], v[202:205], v[18:33]
	ds_read_b64_tr_b16 v[202:203], v185 offset:0x1600
	ds_read_b64_tr_b16 v[204:205], v185 offset:0x1e00
	v_mfma_f32_32x32x16_bf16 v[18:33], v[156:159], v[206:209], v[18:33]
	ds_read_b64_tr_b16 v[206:207], v185 offset:0x2600
	ds_read_b64_tr_b16 v[208:209], v185 offset:0x2e00
	v_mfma_f32_32x32x16_bf16 v[18:33], v[160:163], v[224:227], v[18:33]
	ds_read_b64_tr_b16 v[224:225], v185 offset:0x3600
	ds_read_b64_tr_b16 v[226:227], v185 offset:0x3e00
	s_waitcnt lgkmcnt(0)
	v_mfma_f32_32x32x16_bf16 v[2:17], v[148:151], v[172:175], v[2:17]
	s_cmp_le_i32 s7, s6
	v_mfma_f32_32x32x16_bf16 v[2:17], v[152:155], v[202:205], v[2:17]
	v_mfma_f32_32x32x16_bf16 v[2:17], v[156:159], v[206:209], v[2:17]
	v_mfma_f32_32x32x16_bf16 v[2:17], v[160:163], v[224:227], v[2:17]
	s_cbranch_scc1 .LBB0_91
; __device__ __forceinline__ void mask_tile(f32x16& p0, f32x16& p1, int dq, unsigned W) {
;     const float NEG = -__builtin_inff();
; #pragma unroll
;     for (int r = 0; r < 16; ++r) {
;         const int c = (r & 3) + 8 * (r >> 2);
;         if ((unsigned)(dq - c) >= W) p0[r] = NEG;
;         if ((unsigned)(dq - c - 32) >= W) p1[r] = NEG;
;     }
; }
	v_add_u32_e32 v148, 0x4000007b, v197
	v_cmp_gt_u32_e32 vcc, 2.0, v148
	v_add_u32_e32 v148, 0x5b, v197
	s_nop 0
	v_cndmask_b32_e32 v82, v220, v82, vcc
	v_cmp_lt_u32_e32 vcc, s33, v148
	v_add_u32_e32 v148, 0x7a, v197
	s_nop 0
	v_cndmask_b32_e32 v66, v220, v66, vcc
	v_cmp_lt_u32_e32 vcc, s33, v148
	v_add_u32_e32 v148, 0x5a, v197
	s_nop 0
	v_cndmask_b32_e32 v83, v220, v83, vcc
	v_cmp_lt_u32_e32 vcc, s33, v148
	v_add_u32_e32 v148, 0x79, v197
	s_nop 0
	v_cndmask_b32_e32 v67, v220, v67, vcc
	v_cmp_lt_u32_e32 vcc, s33, v148
	v_add_u32_e32 v148, 0x59, v197
	s_nop 0
	v_cndmask_b32_e32 v84, v220, v84, vcc
	v_cmp_lt_u32_e32 vcc, s33, v148
	v_add_u32_e32 v148, 0x78, v197
	s_nop 0
	v_cndmask_b32_e32 v68, v220, v68, vcc
	v_cmp_lt_u32_e32 vcc, s33, v148
	v_add_u32_e32 v148, 0x58, v197
	s_nop 0
	v_cndmask_b32_e32 v85, v220, v85, vcc
	v_cmp_lt_u32_e32 vcc, s33, v148
	v_add_u32_e32 v148, 0x73, v197
	s_nop 0
	v_cndmask_b32_e32 v69, v220, v69, vcc
	v_cmp_lt_u32_e32 vcc, s33, v148
	v_add_u32_e32 v148, 0x53, v197
	s_nop 0
	v_cndmask_b32_e32 v86, v220, v86, vcc
	v_cmp_lt_u32_e32 vcc, s33, v148
	v_add_u32_e32 v148, 0x72, v197
	s_nop 0
	v_cndmask_b32_e32 v70, v220, v70, vcc
	v_cmp_lt_u32_e32 vcc, s33, v148
	v_add_u32_e32 v148, 0x52, v197
	s_nop 0
	v_cndmask_b32_e32 v87, v220, v87, vcc
	v_cmp_lt_u32_e32 vcc, s33, v148
	v_add_u32_e32 v148, 0x71, v197
	s_nop 0
	v_cndmask_b32_e32 v71, v220, v71, vcc
	v_cmp_lt_u32_e32 vcc, s33, v148
	v_add_u32_e32 v148, 0x51, v197
	s_nop 0
	v_cndmask_b32_e32 v88, v220, v88, vcc
	v_cmp_lt_u32_e32 vcc, s33, v148
	v_add_u32_e32 v148, 0x70, v197
	s_nop 0
	v_cndmask_b32_e32 v72, v220, v72, vcc
	v_cmp_lt_u32_e32 vcc, s33, v148
	v_add_u32_e32 v148, 0x50, v197
	s_nop 0
	v_cndmask_b32_e32 v89, v220, v89, vcc
	v_cmp_lt_u32_e32 vcc, s33, v148
	v_add_u32_e32 v148, 0x6b, v197
	s_nop 0
	v_cndmask_b32_e32 v73, v220, v73, vcc
	v_cmp_lt_u32_e32 vcc, s33, v148
	v_add_u32_e32 v148, 0x4b, v197
	s_nop 0
	v_cndmask_b32_e32 v90, v220, v90, vcc
	v_cmp_lt_u32_e32 vcc, s33, v148
	v_add_u32_e32 v148, 0x6a, v197
	s_nop 0
	v_cndmask_b32_e32 v74, v220, v74, vcc
	v_cmp_lt_u32_e32 vcc, s33, v148
	v_add_u32_e32 v148, 0x4a, v197
	s_nop 0
	v_cndmask_b32_e32 v91, v220, v91, vcc
	v_cmp_lt_u32_e32 vcc, s33, v148
	v_add_u32_e32 v148, 0x69, v197
	s_nop 0
	v_cndmask_b32_e32 v75, v220, v75, vcc
	v_cmp_lt_u32_e32 vcc, s33, v148
	v_add_u32_e32 v148, 0x49, v197
	s_nop 0
	v_cndmask_b32_e32 v92, v220, v92, vcc
	v_cmp_lt_u32_e32 vcc, s33, v148
	v_add_u32_e32 v148, 0x68, v197
	s_nop 0
	v_cndmask_b32_e32 v76, v220, v76, vcc
	v_cmp_lt_u32_e32 vcc, s33, v148
	v_add_u32_e32 v148, 0x48, v197
	s_nop 0
	v_cndmask_b32_e32 v93, v220, v93, vcc
	v_cmp_lt_u32_e32 vcc, s33, v148
	v_add_u32_e32 v148, 0x63, v197
	s_nop 0
	v_cndmask_b32_e32 v77, v220, v77, vcc
	v_cmp_lt_u32_e32 vcc, s33, v148
	v_add_u32_e32 v148, 0x43, v197
	s_nop 0
	v_cndmask_b32_e32 v94, v220, v94, vcc
	v_cmp_lt_u32_e32 vcc, s33, v148
	v_add_u32_e32 v148, 0x62, v197
	s_nop 0
	v_cndmask_b32_e32 v78, v220, v78, vcc
	v_cmp_lt_u32_e32 vcc, s33, v148
	v_add_u32_e32 v148, 0x42, v197
	s_nop 0
	v_cndmask_b32_e32 v95, v220, v95, vcc
	v_cmp_lt_u32_e32 vcc, s33, v148
	v_add_u32_e32 v148, 0x61, v197
	s_nop 0
	v_cndmask_b32_e32 v79, v220, v79, vcc
	v_cmp_lt_u32_e32 vcc, s33, v148
	v_add_u32_e32 v148, 0x41, v197
	s_nop 0
	v_cndmask_b32_e32 v96, v220, v96, vcc
	v_cmp_lt_u32_e32 vcc, s33, v148
	v_add_u32_e32 v148, 0x60, v197
	s_nop 0
	v_cndmask_b32_e32 v80, v220, v80, vcc
	v_cmp_lt_u32_e32 vcc, s33, v148
	v_add_u32_e32 v148, 64, v197
	s_nop 0
	v_cndmask_b32_e32 v97, v220, v97, vcc
	v_cmp_lt_u32_e32 vcc, s33, v148
	s_nop 1
	v_cndmask_b32_e32 v81, v220, v81, vcc

; __device__ __forceinline__ void partialSM(f32x16& p0, f32x16& p1, float& m_reg, float& mn, float& alpha, bool rs) {
;     ...
;     const float mnL = rs ? -mn * C2 : -__builtin_inff();
;     for (int r = 0; r < 16; ++r) p0[r] = fmaf(p0[r], C2, mnL); for (int r = 0; r < 16; ++r) p1[r] = fmaf(p1[r], C2, mnL);
;     for (int r = 0; r < 16; ++r) p0[r] = __builtin_amdgcn_exp2f(p0[r]);
.LBB0_95:
	v_cndmask_b32_e64 v179, v148, v198, s[42:43]
	v_mul_f32_e32 v148, 0xbe0293ee, v179
	v_cndmask_b32_e64 v180, v220, v148, s[40:41]
	v_fmamk_f32 v82, v82, 0x3e0293ee, v180
	v_fmamk_f32 v83, v83, 0x3e0293ee, v180
	v_fmamk_f32 v84, v84, 0x3e0293ee, v180
	v_fmamk_f32 v85, v85, 0x3e0293ee, v180
	v_fmamk_f32 v86, v86, 0x3e0293ee, v180
	v_fmamk_f32 v87, v87, 0x3e0293ee, v180
	v_fmamk_f32 v88, v88, 0x3e0293ee, v180
	v_fmamk_f32 v89, v89, 0x3e0293ee, v180
	v_fmamk_f32 v90, v90, 0x3e0293ee, v180
	v_fmamk_f32 v91, v91, 0x3e0293ee, v180
	v_fmamk_f32 v92, v92, 0x3e0293ee, v180
	v_fmamk_f32 v93, v93, 0x3e0293ee, v180
	v_fmamk_f32 v94, v94, 0x3e0293ee, v180
	v_fmamk_f32 v95, v95, 0x3e0293ee, v180
	v_fmamk_f32 v96, v96, 0x3e0293ee, v180
	v_fmamk_f32 v97, v97, 0x3e0293ee, v180
	v_exp_f32_e32 v148, v82
	v_exp_f32_e32 v163, v83
	v_exp_f32_e32 v149, v84
	v_exp_f32_e32 v162, v85
	v_exp_f32_e32 v150, v86
	v_exp_f32_e32 v161, v87
	v_exp_f32_e32 v151, v88
	v_exp_f32_e32 v160, v89
	v_exp_f32_e32 v152, v90
	v_exp_f32_e32 v159, v91
	v_exp_f32_e32 v153, v92
	v_exp_f32_e32 v158, v93
	v_exp_f32_e32 v154, v94
	v_exp_f32_e32 v157, v95
	v_exp_f32_e32 v155, v96
	v_exp_f32_e32 v156, v97
	v_fmamk_f32 v203, v73, 0x3e0293ee, v180
	v_fmamk_f32 v204, v74, 0x3e0293ee, v180
	v_fmamk_f32 v208, v66, 0x3e0293ee, v180
	v_fmamk_f32 v209, v67, 0x3e0293ee, v180
	v_fmamk_f32 v223, v68, 0x3e0293ee, v180
	v_fmamk_f32 v224, v69, 0x3e0293ee, v180
	v_fmamk_f32 v225, v70, 0x3e0293ee, v180
	v_fmamk_f32 v198, v71, 0x3e0293ee, v180
	v_fmamk_f32 v201, v72, 0x3e0293ee, v180
	v_fmamk_f32 v205, v75, 0x3e0293ee, v180
	v_fmamk_f32 v206, v76, 0x3e0293ee, v180
	v_fmamk_f32 v207, v77, 0x3e0293ee, v180
	v_fmamk_f32 v181, v78, 0x3e0293ee, v180
	v_fmamk_f32 v226, v79, 0x3e0293ee, v180
	v_fmamk_f32 v227, v80, 0x3e0293ee, v180
	v_fmac_f32_e32 v180, 0x3e0293ee, v81
	s_waitcnt lgkmcnt(0)
	s_barrier
; __device__ __forceinline__ void finishSM(f32x16& p0, f32x16& p1, float alpha, float& l_reg, bf16x8& pa0, bf16x8& pa1, bf16x8& pa2, bf16x8& pa3) {
;     for (int r = 0; r < 16; ++r) p1[r] = __builtin_amdgcn_exp2f(p1[r]);
;     float ps = 0; for (int r = 0; r < 16; ++r) ps += p0[r]; for (int r = 0; r < 16; ++r) ps += p1[r];
;     { auto rr = __builtin_amdgcn_permlane32_swap(__float_as_uint(ps), __float_as_uint(ps), false, false);
;       ps = __uint_as_float(rr[0]) + __uint_as_float(rr[1]); }
;     l_reg = l_reg * alpha + ps;
;     ...
;     PK4(p0, 0, pa0); PK4(p0, 8, pa1); PK4(p1, 0, pa2); PK4(p1, 8, pa3);
;     ...
; }
; template <int KB>
; __device__ __forceinline__ void qkt(f32x16& p0, f32x16& p1, const char* K_lds, int r32, int hi, const bf16x8* qr) {
;     p0 = f32x16{}; p1 = f32x16{};
;     const char* kb[4];
; #pragma unroll
;     for (int dd = 0; dd < 4; ++dd) kb[dd] = K_lds + KB * SHM_K + KSWZ(r32, (dd * 16 + hi * 8) * 2);
; #pragma unroll
;     for (int d0 = 0; d0 < 8; ++d0) { const char* a = kb[d0 & 3] + (d0 >> 2) * 128;
;         bf16x8 b0 = *reinterpret_cast<const bf16x8*>(a);
;         bf16x8 b1 = *reinterpret_cast<const bf16x8*>(a + 32 * 256);
;         p0 = __builtin_amdgcn_mfma_f32_32x32x16_bf16(b0, qr[d0], p0, 0, 0, 0);
;         p1 = __builtin_amdgcn_mfma_f32_32x32x16_bf16(b1, qr[d0], p1, 0, 0, 0); }
	s_waitcnt vmcnt(0)
	ds_read_b128 v[66:69], v169 offset:32768
	ds_read_b128 v[70:73], v169 offset:40960
	ds_read_b128 v[172:175], v193 offset:32768
	ds_read_b128 v[228:231], v193 offset:40960
	v_exp_f32_e32 v198, v198
	v_exp_f32_e32 v201, v201
	v_exp_f32_e32 v214, v204
	v_exp_f32_e32 v205, v205
	v_exp_f32_e32 v206, v206
	v_exp_f32_e32 v207, v207
	v_exp_f32_e32 v181, v181
	v_exp_f32_e32 v215, v226
	v_exp_f32_e32 v216, v227
	v_exp_f32_e32 v180, v180
	v_exp_f32_e32 v218, v209
	v_exp_f32_e32 v209, v203
	v_add_f32_e32 v203, 0, v148
	v_add_f32_e32 v203, v163, v203
	v_add_f32_e32 v203, v149, v203
	v_add_f32_e32 v203, v162, v203
	v_add_f32_e32 v203, v150, v203
	v_add_f32_e32 v203, v161, v203
	v_add_f32_e32 v203, v151, v203
	v_add_f32_e32 v203, v160, v203
	s_waitcnt lgkmcnt(3)
	v_mfma_f32_32x32x16_bf16 v[82:97], v[66:69], v[132:135], 0
	v_add_f32_e32 v203, v152, v203
	v_add_f32_e32 v203, v159, v203
	v_add_f32_e32 v203, v153, v203
	v_add_f32_e32 v203, v158, v203
	s_waitcnt lgkmcnt(2)
	v_mfma_f32_32x32x16_bf16 v[66:81], v[70:73], v[132:135], 0
	v_exp_f32_e32 v217, v208
	v_add_f32_e32 v203, v154, v203
	v_add_f32_e32 v203, v157, v203
	v_exp_f32_e32 v219, v223
	s_waitcnt lgkmcnt(1)
	v_mfma_f32_32x32x16_bf16 v[82:97], v[172:175], v[128:131], v[82:97]
	v_add_f32_e32 v203, v155, v203
	v_exp_f32_e32 v222, v224
	v_add_f32_e32 v203, v156, v203
	v_exp_f32_e32 v208, v225
	s_waitcnt lgkmcnt(0)
	v_mfma_f32_32x32x16_bf16 v[66:81], v[228:231], v[128:131], v[66:81]
	v_add_f32_e32 v203, v217, v203
	v_add_f32_e32 v203, v218, v203
	v_add_f32_e32 v203, v219, v203
	v_add_f32_e32 v203, v222, v203
	ds_read_b128 v[172:175], v194 offset:32768
	ds_read_b128 v[228:231], v194 offset:40960
	s_waitcnt lgkmcnt(1)
	v_mfma_f32_32x32x16_bf16 v[82:97], v[172:175], v[124:127], v[82:97]
	v_add_f32_e32 v203, v208, v203
	v_add_f32_e32 v203, v198, v203
	v_add_f32_e32 v203, v201, v203
	v_add_f32_e32 v203, v209, v203
	s_waitcnt lgkmcnt(0)
	v_mfma_f32_32x32x16_bf16 v[66:81], v[228:231], v[124:127], v[66:81]
	v_add_f32_e32 v203, v214, v203
	v_add_f32_e32 v203, v205, v203
	v_add_f32_e32 v203, v206, v203
	v_add_f32_e32 v203, v207, v203
	ds_read_b128 v[172:175], v195 offset:32768
	ds_read_b128 v[228:231], v195 offset:40960
	s_waitcnt lgkmcnt(1)
	v_mfma_f32_32x32x16_bf16 v[82:97], v[172:175], v[120:123], v[82:97]
	v_add_f32_e32 v203, v181, v203
	v_add_f32_e32 v203, v215, v203
	v_add_f32_e32 v203, v216, v203
	v_add_f32_e32 v203, v180, v203
	s_waitcnt lgkmcnt(0)
	v_mfma_f32_32x32x16_bf16 v[66:81], v[228:231], v[120:123], v[66:81]
	v_mov_b32_e32 v204, v203
	v_cvt_pk_bf16_f32 v148, v148, v163
	v_cvt_pk_bf16_f32 v149, v149, v162
	v_cvt_pk_bf16_f32 v150, v150, v161
	ds_read_b128 v[172:175], v169 offset:32896
	ds_read_b128 v[228:231], v169 offset:41088
	s_waitcnt lgkmcnt(1)
	v_mfma_f32_32x32x16_bf16 v[82:97], v[172:175], v[116:119], v[82:97]
	v_cvt_pk_bf16_f32 v151, v151, v160
	v_cvt_pk_bf16_f32 v152, v152, v159
	v_cvt_pk_bf16_f32 v153, v153, v158
	v_cvt_pk_bf16_f32 v154, v154, v157
	s_waitcnt lgkmcnt(0)
	v_mfma_f32_32x32x16_bf16 v[66:81], v[228:231], v[116:119], v[66:81]
	v_cvt_pk_bf16_f32 v155, v155, v156
	v_cvt_pk_bf16_f32 v156, v217, v218
	v_cvt_pk_bf16_f32 v157, v219, v222
	ds_read_b128 v[172:175], v193 offset:32896
	ds_read_b128 v[228:231], v193 offset:41088
	s_waitcnt lgkmcnt(1)
	v_mfma_f32_32x32x16_bf16 v[82:97], v[172:175], v[112:115], v[82:97]
	v_cvt_pk_bf16_f32 v158, v208, v198
	v_cvt_pk_bf16_f32 v159, v201, v209
	v_cvt_pk_bf16_f32 v160, v214, v205
	s_waitcnt lgkmcnt(0)
	v_mfma_f32_32x32x16_bf16 v[66:81], v[228:231], v[112:115], v[66:81]
	v_cvt_pk_bf16_f32 v161, v206, v207
	v_cvt_pk_bf16_f32 v162, v181, v215
	v_cvt_pk_bf16_f32 v163, v216, v180
	ds_read_b128 v[172:175], v194 offset:32896
	ds_read_b128 v[228:231], v194 offset:41088
	s_waitcnt lgkmcnt(1)
	v_mfma_f32_32x32x16_bf16 v[82:97], v[172:175], v[108:111], v[82:97]
	s_nop 1
	v_permlane32_swap_b32_e32 v203, v204
	v_permlane32_swap_b32_e32 v148, v150
	v_permlane32_swap_b32_e32 v149, v151
	s_waitcnt lgkmcnt(0)
	v_mfma_f32_32x32x16_bf16 v[66:81], v[228:231], v[108:111], v[66:81]
	v_permlane32_swap_b32_e32 v152, v154
	v_permlane32_swap_b32_e32 v153, v155
	v_permlane32_swap_b32_e32 v156, v158
	ds_read_b128 v[172:175], v195 offset:32896
	ds_read_b128 v[228:231], v195 offset:41088
	ds_write_b128 v191, v[100:103]
	ds_write_b128 v192, v[136:139]
	ds_read_b64_tr_b16 v[206:207], v185 offset:0x5000
	ds_read_b64_tr_b16 v[208:209], v185 offset:0x5800
	ds_read_b64_tr_b16 v[224:225], v185 offset:0x6000
	ds_read_b64_tr_b16 v[226:227], v185 offset:0x6800
	s_waitcnt lgkmcnt(7)
	v_mfma_f32_32x32x16_bf16 v[82:97], v[172:175], v[104:107], v[82:97]
	v_permlane32_swap_b32_e32 v157, v159
	v_permlane32_swap_b32_e32 v160, v162
	v_permlane32_swap_b32_e32 v161, v163
	s_waitcnt lgkmcnt(6)
	v_mfma_f32_32x32x16_bf16 v[66:81], v[228:231], v[104:107], v[66:81]
	ds_read_b64_tr_b16 v[172:173], v185 offset:0x4000
	ds_read_b64_tr_b16 v[174:175], v185 offset:0x4800
	ds_read_b64_tr_b16 v[228:229], v185 offset:0x7000
	ds_read_b64_tr_b16 v[230:231], v185 offset:0x7800
	s_cmp_lt_u32 s3, s2
	s_cselect_b64 s[22:23], -1, 0
	s_cmp_ge_u32 s3, s2
	s_cbranch_scc1 .LBB0_97
	v_add_u32_e32 v242, 0x41, v178
	v_add_u32_e32 v246, 0x61, v178
	v_ashrrev_i32_e32 v243, 31, v242
	v_ashrrev_i32_e32 v247, 31, v246
	v_lshlrev_b64 v[140:141], 8, v[242:243]
	v_lshlrev_b64 v[142:143], 8, v[246:247]
	v_lshl_add_u64 v[242:243], v[170:171], 0, v[140:141]
	v_lshl_add_u64 v[246:247], v[170:171], 0, v[142:143]
	v_lshl_add_u64 v[140:141], v[176:177], 0, v[140:141]
	v_lshl_add_u64 v[144:145], v[176:177], 0, v[142:143]
	global_load_dwordx4 v[242:245], v[242:243], off
	s_nop 0
	global_load_dwordx4 v[246:249], v[246:247], off
	s_nop 0
	global_load_dwordx4 v[140:143], v[140:141], off
	s_nop 0
	global_load_dwordx4 v[144:147], v[144:145], off
	s_mov_b32 s100, 1
